# weight-conversion routine used in the barrier slack after the first gate/up GEMM: the 26 serialized per-row gain loads (load, vmcnt(0), mul) hoisted into independent registers with one wait
# baseline (speedup 1.0000x reference)
; #define LAS __attribute__((address_space(3)))
; __device__ __forceinline__ void tr_item(const float* W, int ldw, int k0, int n0, const float* kscale, bf16_t* WT, int ldt, int drow0, int dk0, LAS float* scr, int lane) {
;     float wv[32];
; #pragma unroll
;     for (int i = 0; i < 32; ++i) wv[i] = W[(size_t)(k0 + 2 * i + (lane >> 5)) * ldw + n0 + (lane & 31)];
;     if (kscale) {
; #pragma unroll
;         for (int i = 0; i < 32; ++i) wv[i] *= kscale[k0 + 2 * i + (lane >> 5)]; }
; __device__ __forceinline__ void convert_item(const ConvSrc& c, bf16_t* Wb, int it, LAS float* scr, int lane) {
;     const float* W; int ldw, k0, n0; const float* ks = nullptr; bf16_t* WT; int ldt, drow, dk0; int r = it;
;     if (r < 2 * CI_GU) { const int second = r >= CI_GU; if (second) r -= CI_GU; const int kb = r / 176, nb = r % 176; n0 = nb * 32;
;         const int j = n0 < DFF ? n0 : n0 - DFF; drow = 256 * (j >> 7) + (n0 < DFF ? 0 : 128) + (j & 127);
;         W = second ? c.gu2 : c.gu1; ldw = 2 * DFF; k0 = kb * 64; ks = second ? c.n3 : c.n1; WT = Wb + (second ? O_WGU2 : O_WGU1); ldt = DM; dk0 = kb * 64; }
.LBB0_144:
	s_mul_hi_i32 s2, s14, 0x2e8ba2e9
	s_lshr_b32 s3, s2, 31
	s_ashr_i32 s2, s2, 5
	s_add_i32 s2, s2, s3
	s_mul_i32 s18, s2, 0xffffea00
	s_mul_i32 s3, s2, 0xffffff50
	s_add_i32 s20, s16, s18
	s_add_i32 s3, s14, s3
	s_add_i32 s18, s20, 0xfffff500
	s_cmpk_lt_i32 s3, 0x58
	s_cselect_b32 s3, s20, s18
	s_cselect_b32 s18, 0, 0x80
	s_lshl_b32 s2, s2, 6
	s_ashr_i32 s21, s20, 31
	v_lshl_add_u64 v[12:13], s[20:21], 2, v[0:1]
	v_or_b32_e32 v14, s2, v4
	v_mad_i64_i32 v[16:17], s[20:21], v14, s83, v[12:13]
	global_load_dword v11, v[16:17], off
	v_or_b32_e32 v16, 2, v14
	v_mad_i64_i32 v[16:17], s[20:21], v16, s83, v[12:13]
	global_load_dword v18, v[16:17], off
	v_or_b32_e32 v16, 4, v14
	v_mad_i64_i32 v[16:17], s[20:21], v16, s83, v[12:13]
	global_load_dword v19, v[16:17], off
	v_or_b32_e32 v16, 6, v14
	v_mad_i64_i32 v[16:17], s[20:21], v16, s83, v[12:13]
	global_load_dword v20, v[16:17], off
	v_or_b32_e32 v16, 8, v14
	v_mad_i64_i32 v[16:17], s[20:21], v16, s83, v[12:13]
	global_load_dword v21, v[16:17], off
	v_or_b32_e32 v16, 10, v14
	v_mad_i64_i32 v[16:17], s[20:21], v16, s83, v[12:13]
	global_load_dword v22, v[16:17], off
	v_or_b32_e32 v16, 12, v14
	v_mad_i64_i32 v[16:17], s[20:21], v16, s83, v[12:13]
	global_load_dword v23, v[16:17], off
	v_or_b32_e32 v16, 14, v14
	v_mad_i64_i32 v[16:17], s[20:21], v16, s83, v[12:13]
	global_load_dword v24, v[16:17], off
	v_or_b32_e32 v16, 16, v14
	v_mad_i64_i32 v[16:17], s[20:21], v16, s83, v[12:13]
	global_load_dword v25, v[16:17], off
	v_or_b32_e32 v16, 18, v14
	v_mad_i64_i32 v[16:17], s[20:21], v16, s83, v[12:13]
	global_load_dword v26, v[16:17], off
	v_or_b32_e32 v16, 20, v14
	v_mad_i64_i32 v[16:17], s[20:21], v16, s83, v[12:13]
	global_load_dword v27, v[16:17], off
	v_or_b32_e32 v16, 22, v14
	v_mad_i64_i32 v[16:17], s[20:21], v16, s83, v[12:13]
	global_load_dword v28, v[16:17], off
	v_or_b32_e32 v16, 24, v14
	v_mad_i64_i32 v[16:17], s[20:21], v16, s83, v[12:13]
	global_load_dword v30, v[16:17], off
	v_or_b32_e32 v16, 26, v14
	v_mad_i64_i32 v[16:17], s[20:21], v16, s83, v[12:13]
	global_load_dword v32, v[16:17], off
	v_or_b32_e32 v16, 28, v14
	v_mad_i64_i32 v[16:17], s[20:21], v16, s83, v[12:13]
	global_load_dword v39, v[16:17], off
	v_or_b32_e32 v16, 30, v14
	v_mad_i64_i32 v[16:17], s[20:21], v16, s83, v[12:13]
	global_load_dword v42, v[16:17], off
	v_or_b32_e32 v16, 32, v14
	v_mad_i64_i32 v[16:17], s[20:21], v16, s83, v[12:13]
	global_load_dword v43, v[16:17], off
	v_or_b32_e32 v16, 34, v14
	v_mad_i64_i32 v[16:17], s[20:21], v16, s83, v[12:13]
	global_load_dword v44, v[16:17], off
	v_or_b32_e32 v16, 36, v14
	v_mad_i64_i32 v[16:17], s[20:21], v16, s83, v[12:13]
	global_load_dword v45, v[16:17], off
	v_or_b32_e32 v16, 38, v14
	v_mad_i64_i32 v[16:17], s[20:21], v16, s83, v[12:13]
	global_load_dword v46, v[16:17], off
	v_or_b32_e32 v16, 40, v14
	v_mad_i64_i32 v[16:17], s[20:21], v16, s83, v[12:13]
	global_load_dword v47, v[16:17], off
	v_or_b32_e32 v16, 42, v14
	v_mad_i64_i32 v[16:17], s[20:21], v16, s83, v[12:13]
	global_load_dword v48, v[16:17], off
	v_or_b32_e32 v16, 44, v14
	v_mad_i64_i32 v[16:17], s[20:21], v16, s83, v[12:13]
	global_load_dword v49, v[16:17], off
	v_or_b32_e32 v16, 46, v14
	v_mad_i64_i32 v[16:17], s[20:21], v16, s83, v[12:13]
	global_load_dword v50, v[16:17], off
	v_or_b32_e32 v16, 48, v14
	v_mad_i64_i32 v[16:17], s[20:21], v16, s83, v[12:13]
	global_load_dword v51, v[16:17], off
	v_or_b32_e32 v16, 50, v14
	v_mad_i64_i32 v[16:17], s[20:21], v16, s83, v[12:13]
	global_load_dword v52, v[16:17], off
	v_or_b32_e32 v16, 52, v14
	v_mad_i64_i32 v[16:17], s[20:21], v16, s83, v[12:13]
	global_load_dword v53, v[16:17], off
	v_or_b32_e32 v16, 54, v14
	v_mad_i64_i32 v[16:17], s[20:21], v16, s83, v[12:13]
	global_load_dword v54, v[16:17], off
	v_or_b32_e32 v16, 56, v14
	v_mad_i64_i32 v[16:17], s[20:21], v16, s83, v[12:13]
	global_load_dword v55, v[16:17], off
	v_or_b32_e32 v16, 58, v14
	v_mad_i64_i32 v[16:17], s[20:21], v16, s83, v[12:13]
	global_load_dword v56, v[16:17], off
	v_or_b32_e32 v16, 60, v14
	v_mad_i64_i32 v[16:17], s[20:21], v16, s83, v[12:13]
	v_ashrrev_i32_e32 v15, 31, v14
	global_load_dword v16, v[16:17], off
	v_or_b32_e32 v17, 62, v14
	v_mad_i64_i32 v[12:13], s[20:21], v17, s83, v[12:13]
	v_lshl_add_u64 v[40:41], v[14:15], 2, s[0:1]
	global_load_dword v57, v[12:13], off
	global_load_dword v14, v[40:41], off offset:240
	s_lshl_b32 s19, s3, 1
	global_load_dword v12, v[40:41], off
	s_and_b32 s3, s3, 0x60
	s_and_b32 s19, s19, 0xffffff00
	s_or_b32 s3, s3, s18
	s_or_b32 s18, s3, s19
	s_ashr_i32 s3, s2, 31
	s_add_i32 s14, s14, s15
	s_add_i32 s16, s16, s17
	s_cmpk_lt_i32 s14, 0xa65
	s_waitcnt vmcnt(1)
	v_mul_f32_e32 v14, v16, v14
	global_load_dword v16, v[40:41], off offset:248
	s_waitcnt vmcnt(1)
	v_mul_f32_e32 v58, v11, v12
	global_load_dword v11, v[40:41], off offset:8
	global_load_dword v12, v[40:41], off offset:232
	s_waitcnt vmcnt(2)
	v_mul_f32_e32 v16, v57, v16
	s_waitcnt vmcnt(1)
	v_mul_f32_e32 v59, v18, v11
	global_load_dword v11, v[40:41], off offset:16
	s_waitcnt vmcnt(1)
	v_mul_f32_e32 v12, v56, v12
	s_waitcnt vmcnt(0)
; #define LAS __attribute__((address_space(3)))
; __device__ __forceinline__ unsigned cvtpk(float lo, float hi) { f32x2_t v = {lo, hi}; bf16x2_t b = __builtin_convertvector(v, bf16x2_t); return __builtin_bit_cast(unsigned, b); }
; #define LDS_WAIT() asm volatile("s_waitcnt lgkmcnt(0)" ::: "memory")
; __device__ __forceinline__ void tr_item(const float* W, int ldw, int k0, int n0, const float* kscale, bf16_t* WT, int ldt, int drow0, int dk0, LAS float* scr, int lane) {
;     float wv[32];
; #pragma unroll
;     for (int i = 0; i < 32; ++i) wv[i] = W[(size_t)(k0 + 2 * i + (lane >> 5)) * ldw + n0 + (lane & 31)];
;     if (kscale) {
; #pragma unroll
;         for (int i = 0; i < 32; ++i) wv[i] *= kscale[k0 + 2 * i + (lane >> 5)]; }
; #pragma unroll
;     for (int i = 0; i < 32; ++i) scr[(2 * i + (lane >> 5)) * 33 + (lane & 31)] = wv[i];
;     LDS_WAIT(); asm volatile("" ::: "memory");
;     const int c = lane & 7;
; #pragma unroll
;     for (int j = 0; j < 4; ++j) { const int n = (lane >> 3) + 8 * j; const LAS float* s = scr + (8 * c) * 33 + n;
;         u32x4 o; o.x = cvtpk(s[0 * 33], s[1 * 33]); o.y = cvtpk(s[2 * 33], s[3 * 33]); o.z = cvtpk(s[4 * 33], s[5 * 33]); o.w = cvtpk(s[6 * 33], s[7 * 33]);
;         *(u32x4*)(WT + (size_t)(drow0 + n) * ldt + dk0 + 8 * c) = o; }
;     LDS_WAIT(); asm volatile("" ::: "memory");
; }
	v_mul_f32_e32 v60, v19, v11
	global_load_dword v64, v[40:41], off offset:24
	global_load_dword v65, v[40:41], off offset:32
	global_load_dword v66, v[40:41], off offset:40
	global_load_dword v67, v[40:41], off offset:48
	global_load_dword v68, v[40:41], off offset:56
	global_load_dword v69, v[40:41], off offset:64
	global_load_dword v70, v[40:41], off offset:72
	global_load_dword v71, v[40:41], off offset:80
	global_load_dword v72, v[40:41], off offset:88
	global_load_dword v73, v[40:41], off offset:96
	global_load_dword v74, v[40:41], off offset:104
	global_load_dword v75, v[40:41], off offset:112
	global_load_dword v76, v[40:41], off offset:120
	global_load_dword v77, v[40:41], off offset:128
	global_load_dword v78, v[40:41], off offset:136
	global_load_dword v79, v[40:41], off offset:144
	global_load_dword v80, v[40:41], off offset:152
	global_load_dword v81, v[40:41], off offset:160
	global_load_dword v82, v[40:41], off offset:168
	global_load_dword v83, v[40:41], off offset:176
	global_load_dword v84, v[40:41], off offset:184
	global_load_dword v85, v[40:41], off offset:192
	global_load_dword v86, v[40:41], off offset:200
	global_load_dword v87, v[40:41], off offset:208
	global_load_dword v88, v[40:41], off offset:216
	global_load_dword v89, v[40:41], off offset:224
	s_waitcnt vmcnt(0)
	v_mul_f32_e32 v61, v20, v64
	v_mul_f32_e32 v33, v21, v65
	v_mul_f32_e32 v35, v22, v66
	v_mul_f32_e32 v37, v23, v67
	v_mul_f32_e32 v38, v24, v68
	v_mul_f32_e32 v29, v25, v69
	v_mul_f32_e32 v31, v26, v70
	v_mul_f32_e32 v34, v27, v71
	v_mul_f32_e32 v36, v28, v72
	v_mul_f32_e32 v25, v30, v73
	v_mul_f32_e32 v27, v32, v74
	v_mul_f32_e32 v30, v39, v75
	v_add_u32_e32 v39, 0x400, v10
	v_mul_f32_e32 v32, v42, v76
	v_mul_f32_e32 v21, v43, v77
	v_mul_f32_e32 v23, v44, v78
	v_mul_f32_e32 v26, v45, v79
	v_mul_f32_e32 v28, v46, v80
	v_mul_f32_e32 v17, v47, v81
	v_mul_f32_e32 v19, v48, v82
	v_mul_f32_e32 v22, v49, v83
	v_mul_f32_e32 v24, v50, v84
	v_mul_f32_e32 v13, v51, v85
	v_mul_f32_e32 v15, v52, v86
	v_mul_f32_e32 v18, v53, v87
	v_mul_f32_e32 v20, v54, v88
	ds_write2_b32 v10, v58, v59 offset1:66
	ds_write2_b32 v10, v60, v61 offset0:132 offset1:198
	ds_write2_b32 v39, v33, v35 offset0:8 offset1:74
	ds_write2_b32 v39, v37, v38 offset0:140 offset1:206
	v_add_u32_e32 v33, 0x800, v10
	ds_write2_b32 v33, v29, v31 offset0:16 offset1:82
	ds_write2_b32 v33, v34, v36 offset0:148 offset1:214
	v_add_u32_e32 v29, 0xc00, v10
	ds_write2_b32 v29, v25, v27 offset0:24 offset1:90
	ds_write2_b32 v29, v30, v32 offset0:156 offset1:222
	v_add_u32_e32 v25, 0x1000, v10
	ds_write2_b32 v25, v21, v23 offset0:32 offset1:98
	ds_write2_b32 v25, v26, v28 offset0:164 offset1:230
	v_add_u32_e32 v21, 0x1400, v10
	ds_write2_b32 v21, v17, v19 offset0:40 offset1:106
	ds_write2_b32 v21, v22, v24 offset0:172 offset1:238
	v_add_u32_e32 v17, 0x1800, v10
	ds_write2_b32 v17, v13, v15 offset0:48 offset1:114
	ds_write2_b32 v17, v18, v20 offset0:180 offset1:246
	v_add_u32_e32 v13, 0x1c00, v10
	v_or_b32_e32 v34, s18, v5
	v_ashrrev_i32_e32 v35, 31, v34
	v_lshlrev_b64 v[34:35], 11, v[34:35]
	v_mul_f32_e32 v11, v55, v89
	ds_write2_b32 v13, v11, v12 offset0:56 offset1:122
	ds_write2_b32 v13, v14, v16 offset0:188 offset1:254
	s_waitcnt lgkmcnt(0)
	ds_read2_b32 v[18:19], v6 offset0:33 offset1:41
	ds_read2_b32 v[20:21], v6 offset1:8
	ds_read2_b32 v[22:23], v6 offset0:66 offset1:74
	ds_read2_b32 v[24:25], v6 offset0:99 offset1:107
	ds_read2_b32 v[26:27], v6 offset0:132 offset1:140
	ds_read2_b32 v[28:29], v6 offset0:165 offset1:173
	ds_read2_b32 v[30:31], v6 offset0:198 offset1:206
	ds_read2_b32 v[32:33], v6 offset0:231 offset1:239
	v_lshl_add_u64 v[16:17], s[2:3], 1, v[2:3]
	s_waitcnt lgkmcnt(6)
	v_cvt_pk_bf16_f32 v12, v20, v18
	s_waitcnt lgkmcnt(4)
	v_cvt_pk_bf16_f32 v13, v22, v24
	s_waitcnt lgkmcnt(2)
	v_cvt_pk_bf16_f32 v14, v26, v28
	s_waitcnt lgkmcnt(0)
	v_cvt_pk_bf16_f32 v15, v30, v32
	v_lshl_add_u64 v[34:35], v[16:17], 0, v[34:35]
	v_or_b32_e32 v18, s18, v7
	global_store_dwordx4 v[34:35], v[12:15], off
	v_or_b32_e32 v34, s18, v8
	v_ashrrev_i32_e32 v35, 31, v34
	v_cvt_pk_bf16_f32 v12, v21, v19
	v_ashrrev_i32_e32 v19, 31, v18
	v_lshlrev_b64 v[18:19], 11, v[18:19]
	v_cvt_pk_bf16_f32 v13, v23, v25
	v_cvt_pk_bf16_f32 v14, v27, v29
	v_cvt_pk_bf16_f32 v15, v31, v33
	v_lshl_add_u64 v[18:19], v[16:17], 0, v[18:19]
	global_store_dwordx4 v[18:19], v[12:15], off
	ds_read2_b32 v[18:19], v6 offset0:49 offset1:57
	ds_read2_b32 v[20:21], v6 offset0:16 offset1:24
	ds_read2_b32 v[22:23], v6 offset0:82 offset1:90
	ds_read2_b32 v[24:25], v6 offset0:115 offset1:123
	ds_read2_b32 v[26:27], v6 offset0:148 offset1:156
	ds_read2_b32 v[28:29], v6 offset0:181 offset1:189
	ds_read2_b32 v[30:31], v6 offset0:214 offset1:222
	ds_read2_b32 v[32:33], v6 offset0:247 offset1:255
	v_lshlrev_b64 v[34:35], 11, v[34:35]
	s_waitcnt lgkmcnt(6)
	v_cvt_pk_bf16_f32 v12, v20, v18
	s_waitcnt lgkmcnt(4)
	v_cvt_pk_bf16_f32 v13, v22, v24
	s_waitcnt lgkmcnt(2)
	v_cvt_pk_bf16_f32 v14, v26, v28
	s_waitcnt lgkmcnt(0)
	v_cvt_pk_bf16_f32 v15, v30, v32
	v_lshl_add_u64 v[34:35], v[16:17], 0, v[34:35]
	v_or_b32_e32 v18, s18, v9
	global_store_dwordx4 v[34:35], v[12:15], off
	s_nop 1
	v_cvt_pk_bf16_f32 v12, v21, v19
	v_ashrrev_i32_e32 v19, 31, v18
	v_lshlrev_b64 v[18:19], 11, v[18:19]
	v_cvt_pk_bf16_f32 v13, v23, v25
	v_cvt_pk_bf16_f32 v14, v27, v29
	v_cvt_pk_bf16_f32 v15, v31, v33
	v_lshl_add_u64 v[16:17], v[16:17], 0, v[18:19]
	global_store_dwordx4 v[16:17], v[12:15], off
	s_waitcnt lgkmcnt(0)
	s_cbranch_scc1 .LBB0_144
